# MoBA phase B: K/V staging tile double-buffered in LDS (static LDS 65556 -> 79392), one workgroup barrier per key tile instead of two; next tile written right after the barrier
# speedup vs baseline: 1.0038x; 1.0038x over previous
.LBB0_414:
	v_mov_b32_e32 v16, v116
	s_nop 1
	v_permlane16_swap_b32_e32 v116, v16
	v_add_f32_e32 v16, v116, v16
	v_or_b32_e32 v93, v130, v15
	v_mov_b32_e32 v17, v16
	v_cmp_eq_u32_e64 s[38:39], 0, v3
	s_nop 0
	v_permlane32_swap_b32_e32 v16, v17
	v_lshlrev_b32_e32 v92, 2, v93
	s_and_saveexec_b64 s[2:3], s[38:39]
	v_add_f32_e32 v16, v16, v17
	ds_write2st64_b32 v92, v133, v16 offset0:208 offset1:210
	s_or_b64 exec, exec, s[2:3]
	v_mov_b32_e32 v17, v117
	s_nop 1
	v_permlane16_swap_b32_e32 v117, v17
	s_movk_i32 s2, 0x110
	v_add_f32_e32 v17, v117, v17
	v_mul_lo_u32 v16, v93, s2
	s_waitcnt vmcnt(3)
	v_mov_b32_e32 v44, v17
	v_add_u32_e32 v16, v4, v16
	s_nop 0
	v_permlane32_swap_b32_e32 v17, v44
	ds_write_b128 v16, v[76:79] offset:18432
	ds_write_b128 v16, v[80:83] offset:18496
	ds_write_b128 v16, v[84:87] offset:18560
	ds_write_b128 v16, v[88:91] offset:18624
	s_and_saveexec_b64 s[2:3], s[38:39]
	v_add_f32_e32 v17, v17, v44
	v_add_u32_e32 v44, 64, v92
	ds_write2st64_b32 v44, v1, v17 offset0:208 offset1:210
	s_or_b64 exec, exec, s[2:3]
	s_and_b64 vcc, exec, s[48:49]
	ds_write_b128 v16, v[60:63] offset:22784
	ds_write_b128 v16, v[64:67] offset:22848
	ds_write_b128 v16, v[68:71] offset:22912
	ds_write_b128 v16, v[72:75] offset:22976
	s_cbranch_vccz .LBB0_329
	v_mov_b32_e32 v1, v2
	s_lshl_b32 s2, s10, 4
	v_lshl_add_u64 v[12:13], v[12:13], 0, v[0:1]
	s_add_i32 s15, s2, 0xde88
	v_mov_b32_e32 v17, 0xf149f2ca
	v_mov_b32_e32 v16, 0
	v_mov_b32_e32 v1, 0
	s_mov_b64 s[42:43], 0
	s_mov_b64 s[48:49], 0
	v_mov_b32_e32 v219, 0xc290
	v_mov_b32_e32 v222, 0xee20
	v_cmp_lt_u32_e32 vcc, 0x7f, v197
	s_nop 1
	v_cndmask_b32_e32 v219, v219, v222, vcc
	s_mov_b32 s98, 1
	v_add_u32_e32 v220, 0x10020, v5
	v_add_u32_e32 v221, v219, v5
	s_waitcnt vmcnt(0)
	ds_write_b128 v220, v[24:27]
	ds_write_b128 v220, v[20:23] offset:16
	ds_write_b128 v221, v[32:35] offset:9216
	ds_write_b128 v221, v[28:31] offset:9232
	s_add_i32 s2, s10, 1
	s_cmp_ge_i32 s2, s14
	s_cbranch_scc1 .Lmb_pre_done
	v_mov_b32_e32 v52, s15
	ds_read_b32 v153, v52 offset:8
	s_waitcnt lgkmcnt(0)
	v_add_u32_e32 v222, v153, v7
	v_mad_i64_i32 v[224:225], s[2:3], v222, s93, v[12:13]
	global_load_dwordx4 v[20:23], v[224:225], off offset:528
	global_load_dwordx4 v[24:27], v[224:225], off offset:512
	global_load_dwordx4 v[28:31], v[224:225], off offset:1040
	global_load_dwordx4 v[32:35], v[224:225], off offset:1024
.Lmb_pre_done:
	s_branch .LBB0_423

.LBB0_423:
	s_add_i32 s16, s10, 1
	s_cmp_ge_i32 s16, s14
	s_cselect_b64 s[40:41], -1, 0
	s_and_b64 vcc, exec, s[40:41]
	s_waitcnt lgkmcnt(0)
	s_barrier
	v_mov_b32_e32 v52, s15
	ds_read_b32 v77, v52
	ds_read_b32 v153, v52 offset:24
	s_cmp_eq_u32 s98, 0
	s_cselect_b32 s99, 0x10020, 0
	v_add_u32_e32 v220, s99, v5
	s_cselect_b32 s99, 1, 0
	v_mad_u32_u24 v221, v219, s99, v5
	s_cselect_b32 s99, 0, 0x10020
	s_cselect_b32 s100, 0, 0xc290
	s_cselect_b32 s101, 0, 0xee20
	s_xor_b32 s98, s98, 1
	s_cbranch_vccnz .Lmb_last
	s_waitcnt vmcnt(0)
	ds_write_b128 v220, v[24:27]
	ds_write_b128 v220, v[20:23] offset:16
	ds_write_b128 v221, v[32:35] offset:9216
	ds_write_b128 v221, v[28:31] offset:9232
	s_waitcnt lgkmcnt(4)
	s_add_i32 s2, s10, 2
	s_cmp_ge_i32 s2, s14
	s_cbranch_scc1 .LBB0_425
	v_add_u32_e32 v222, v153, v7
	v_mad_i64_i32 v[224:225], s[2:3], v222, s93, v[12:13]
	global_load_dwordx4 v[20:23], v[224:225], off offset:528
	global_load_dwordx4 v[24:27], v[224:225], off offset:512
	global_load_dwordx4 v[28:31], v[224:225], off offset:1040
	global_load_dwordx4 v[32:35], v[224:225], off offset:1024
	s_branch .LBB0_425
.Lmb_last:
	s_waitcnt lgkmcnt(0)
.LBB0_425:
	v_cmp_ne_u32_e32 vcc, 0, v77
	s_cbranch_vccz .LBB0_427
	v_mov_b64_e32 v[58:59], v[42:43]
	v_mov_b64_e32 v[54:55], v[38:39]
	v_mov_b64_e32 v[56:57], v[40:41]
	v_mov_b64_e32 v[52:53], v[36:37]
	v_mov_b32_e32 v76, v129
	s_mov_b64 s[50:51], s[46:47]
	s_mov_b64 s[2:3], s[44:45]
	s_and_saveexec_b64 s[8:9], s[48:49]
	s_cbranch_execz .LBB0_422
	s_branch .LBB0_432

.LBB0_432:
	v_mov_b32_e32 v90, v197
	s_nop 0
	v_and_b32_e32 v36, 15, v90
	v_bfe_u32 v91, v90, 4, 2
	v_mul_u32_u24_e32 v36, 0x90, v36
	v_lshl_add_u32 v98, v91, 4, v36
	v_add_u32_e32 v98, s99, v98
	ds_read_b128 v[36:39], v98
	ds_read_b128 v[86:89], v98 offset:64
	ds_read_b128 v[78:81], v98 offset:4608
	ds_read_b128 v[94:97], v98 offset:4672
	ds_read_b128 v[40:43], v98 offset:2304
	ds_read_b128 v[82:85], v98 offset:6912
	s_waitcnt lgkmcnt(5)
	v_mfma_f32_16x16x32_bf16 v[36:39], v[36:39], v[44:47], 0
	s_waitcnt lgkmcnt(3)
	v_mfma_f32_16x16x32_bf16 v[78:81], v[78:81], v[44:47], 0
	v_mfma_f32_16x16x32_bf16 v[86:89], v[86:89], v[48:51], v[36:39]
	s_nop 4
	ds_read_b128 v[36:39], v98 offset:2368
	s_waitcnt lgkmcnt(3)
	v_mfma_f32_16x16x32_bf16 v[78:81], v[94:97], v[48:51], v[78:81]
	ds_read_b128 v[94:97], v98 offset:6976
	s_waitcnt lgkmcnt(3)
	v_mfma_f32_16x16x32_bf16 v[40:43], v[40:43], v[44:47], 0
	s_waitcnt lgkmcnt(2)
	v_mfma_f32_16x16x32_bf16 v[82:85], v[82:85], v[44:47], 0
	s_waitcnt lgkmcnt(1)
	v_mfma_f32_16x16x32_bf16 v[38:41], v[36:39], v[48:51], v[40:43]
	v_max_f32_e32 v36, v89, v89
	v_max_f32_e32 v37, v88, v88
	v_max_f32_e32 v36, v37, v36
	s_waitcnt lgkmcnt(0)
	v_mfma_f32_16x16x32_bf16 v[82:85], v[94:97], v[48:51], v[82:85]
	v_bfe_u32 v186, v90, 2, 2
	v_lshlrev_b32_e32 v187, 3, v90
	v_lshl_or_b32 v186, v91, 2, v186
	v_and_b32_e32 v187, 24, v187
	v_mad_u32_u24 v186, v186, s0, v187
	v_add_u32_e32 v187, s101, v186
	v_add_u32_e32 v186, s100, v186
	ds_read_b64_tr_b16 v[154:155], v186 offset:9216
	ds_read_b64_tr_b16 v[156:157], v186 offset:11520
	ds_read_b64_tr_b16 v[158:159], v186 offset:9248
	ds_read_b64_tr_b16 v[160:161], v186 offset:11552
	ds_read_b64_tr_b16 v[162:163], v186 offset:9280
	ds_read_b64_tr_b16 v[164:165], v186 offset:11584
	ds_read_b64_tr_b16 v[166:167], v186 offset:9312
	ds_read_b64_tr_b16 v[168:169], v186 offset:11616
	ds_read_b64_tr_b16 v[170:171], v187 offset:13824
	ds_read_b64_tr_b16 v[172:173], v187 offset:16128
	ds_read_b64_tr_b16 v[174:175], v187 offset:13856
	ds_read_b64_tr_b16 v[176:177], v187 offset:16160
	ds_read_b64_tr_b16 v[178:179], v187 offset:13888
	ds_read_b64_tr_b16 v[180:181], v187 offset:16192
	ds_read_b64_tr_b16 v[182:183], v187 offset:13920
	ds_read_b64_tr_b16 v[184:185], v187 offset:16224
	v_max3_f32 v36, v86, v87, v36
	s_nop 1
	v_max_f32_e32 v37, v41, v41
	v_max_f32_e32 v42, v40, v40
	v_max_f32_e32 v37, v42, v37
	v_max3_f32 v37, v38, v39, v37
	v_max3_f32 v36, v36, s28, v37
	v_max_f32_e32 v37, v81, v81
	v_max_f32_e32 v42, v80, v80
	v_max_f32_e32 v37, v42, v37
	v_max_f32_e32 v42, v85, v85
	v_max_f32_e32 v43, v84, v84
	v_max_f32_e32 v42, v43, v42
	v_max3_f32 v37, v78, v79, v37
	v_max3_f32 v42, v82, v83, v42
	v_max3_f32 v36, v36, v37, v42
	v_mov_b32_e32 v37, v36
	s_nop 1
	v_permlane16_swap_b32_e32 v36, v37
	v_max_f32_e32 v37, v37, v37
	v_max_f32_e32 v36, v36, v36
	v_max_f32_e32 v36, v36, v37
	v_mov_b32_e32 v37, v36
	s_nop 1
	v_permlane32_swap_b32_e32 v36, v37
	v_max3_f32 v37, v17, v36, v37
	v_mul_f32_e32 v36, 0x3e38aa3b, v37
	v_cmp_ngt_f32_e32 vcc, s36, v37
	v_sub_f32_e32 v17, v17, v37
	v_mul_f32_e32 v17, 0x3e38aa3b, v17
	v_cndmask_b32_e32 v36, 0, v36, vcc
	v_fma_f32 v42, v86, s29, -v36
	v_exp_f32_e32 v86, v42
	v_fma_f32 v43, v87, s29, -v36
	v_exp_f32_e32 v87, v43
	v_fma_f32 v43, v88, s29, -v36
	v_exp_f32_e32 v88, v43
	v_fma_f32 v43, v89, s29, -v36
	v_exp_f32_e32 v89, v43
	v_fma_f32 v38, v38, s29, -v36
	v_add_f32_e32 v42, 0, v86
	v_exp_f32_e32 v94, v38
	v_fma_f32 v39, v39, s29, -v36
	v_add_f32_e32 v42, v87, v42
	v_exp_f32_e32 v39, v39
	v_fma_f32 v40, v40, s29, -v36
	v_add_f32_e32 v42, v88, v42
	v_exp_f32_e32 v95, v40
	v_fma_f32 v40, v41, s29, -v36
	v_add_f32_e32 v42, v89, v42
	v_exp_f32_e32 v96, v40
	v_fma_f32 v40, v78, s29, -v36
	v_add_f32_e32 v38, v94, v42
	v_exp_f32_e32 v97, v40
	v_fma_f32 v40, v79, s29, -v36
	v_add_f32_e32 v38, v39, v38
	v_exp_f32_e32 v98, v40
	v_fma_f32 v40, v80, s29, -v36
	v_add_f32_e32 v38, v95, v38
	v_exp_f32_e32 v99, v40
	v_fma_f32 v40, v81, s29, -v36
	v_add_f32_e32 v38, v96, v38
	v_exp_f32_e32 v100, v40
	v_fma_f32 v40, v82, s29, -v36
	v_add_f32_e32 v38, v97, v38
	v_exp_f32_e32 v101, v40
	v_fma_f32 v40, v83, s29, -v36
	v_add_f32_e32 v38, v98, v38
	v_exp_f32_e32 v102, v40
	v_fma_f32 v40, v84, s29, -v36
	v_add_f32_e32 v38, v99, v38
	v_exp_f32_e32 v103, v40
	v_fma_f32 v36, v85, s29, -v36
	v_add_f32_e32 v38, v100, v38
	v_exp_f32_e32 v104, v36
	v_add_f32_e32 v38, v101, v38
	v_exp_f32_e32 v36, v17
	v_add_f32_e32 v38, v102, v38
	v_add_f32_e32 v38, v103, v38
	v_add_f32_e32 v38, v104, v38
	v_fmac_f32_e32 v38, v16, v36
	v_pk_mul_f32 v[42:43], v[62:63], v[36:37] op_sel_hi:[1,0]
	v_pk_mul_f32 v[40:41], v[60:61], v[36:37] op_sel_hi:[1,0]
	v_pk_mul_f32 v[62:63], v[66:67], v[36:37] op_sel_hi:[1,0]
	v_pk_mul_f32 v[60:61], v[64:65], v[36:37] op_sel_hi:[1,0]
	v_pk_mul_f32 v[66:67], v[70:71], v[36:37] op_sel_hi:[1,0]
	v_pk_mul_f32 v[64:65], v[68:69], v[36:37] op_sel_hi:[1,0]
	v_pk_mul_f32 v[70:71], v[74:75], v[36:37] op_sel_hi:[1,0]
	v_pk_mul_f32 v[68:69], v[72:73], v[36:37] op_sel_hi:[1,0]
	v_cvt_pk_bf16_f32 v72, v86, v87
	v_cvt_pk_bf16_f32 v73, v88, v89
	v_cvt_pk_bf16_f32 v74, v94, v39
	v_cvt_pk_bf16_f32 v75, v95, v96
	v_cvt_pk_bf16_f32 v86, v97, v98
	v_cvt_pk_bf16_f32 v87, v99, v100
	v_cvt_pk_bf16_f32 v88, v101, v102
	v_cvt_pk_bf16_f32 v89, v103, v104
	v_cmp_ne_u32_e32 vcc, 3, v77
	s_waitcnt lgkmcnt(14)
	v_mfma_f32_16x16x32_bf16 v[40:43], v[154:157], v[72:75], v[40:43]
	s_waitcnt lgkmcnt(12)
	v_mfma_f32_16x16x32_bf16 v[78:81], v[158:161], v[72:75], v[60:63]
	s_and_b64 vcc, exec, vcc
	s_waitcnt lgkmcnt(10)
	v_mfma_f32_16x16x32_bf16 v[82:85], v[162:165], v[72:75], v[64:67]
	s_waitcnt lgkmcnt(8)
	v_mfma_f32_16x16x32_bf16 v[72:75], v[166:169], v[72:75], v[68:71]
	s_waitcnt lgkmcnt(6)
	v_mfma_f32_16x16x32_bf16 v[60:63], v[170:173], v[86:89], v[40:43]
	s_waitcnt lgkmcnt(4)
	v_mfma_f32_16x16x32_bf16 v[64:67], v[174:177], v[86:89], v[78:81]
	s_waitcnt lgkmcnt(2)
	v_mfma_f32_16x16x32_bf16 v[68:71], v[178:181], v[86:89], v[82:85]
	s_waitcnt lgkmcnt(0)
	v_mfma_f32_16x16x32_bf16 v[72:75], v[182:185], v[86:89], v[72:75]
	s_cbranch_vccnz .LBB0_421
	v_mov_b32_e32 v16, v38
	v_mov_b32_e32 v17, v38
	s_nop 1
	v_permlane16_swap_b32_e32 v16, v17
	v_add_f32_e32 v39, v16, v17
	v_mov_b32_e32 v40, v39
	s_nop 1
	v_permlane32_swap_b32_e32 v39, v40
	s_and_saveexec_b64 s[10:11], s[42:43]
	s_cbranch_execz .LBB0_420
	v_lshlrev_b32_e32 v41, 2, v1
	ds_read2st64_b32 v[16:17], v41 offset0:208 offset1:210
	v_max_f32_e32 v42, v37, v37
	s_movk_i32 s17, 0x110
	v_mad_u64_u32 v[82:83], s[20:21], v1, s17, v[4:5]
	s_waitcnt lgkmcnt(0)
	v_max_f32_e32 v36, v16, v16
	v_max_f32_e32 v42, v36, v42
	v_sub_f32_e32 v36, v37, v42
	v_sub_f32_e32 v16, v16, v42
	v_mul_f32_e32 v36, 0x3e38aa3b, v36
	v_mul_f32_e32 v16, 0x3e38aa3b, v16
	v_exp_f32_e32 v36, v36
	ds_read_b128 v[78:81], v82 offset:18432
	v_exp_f32_e32 v16, v16
	v_pk_mul_f32 v[84:85], v[62:63], v[36:37] op_sel_hi:[1,0]
	v_pk_mul_f32 v[86:87], v[60:61], v[36:37] op_sel_hi:[1,0]
	s_waitcnt lgkmcnt(0)
	v_pk_fma_f32 v[80:81], v[80:81], v[16:17], v[84:85] op_sel_hi:[1,0,1]
	v_pk_fma_f32 v[78:79], v[78:79], v[16:17], v[86:87] op_sel_hi:[1,0,1]
	ds_write_b128 v82, v[78:81] offset:18432
	ds_read_b128 v[78:81], v82 offset:18496
	v_pk_mul_f32 v[84:85], v[66:67], v[36:37] op_sel_hi:[1,0]
	v_pk_mul_f32 v[86:87], v[64:65], v[36:37] op_sel_hi:[1,0]
	s_waitcnt lgkmcnt(0)
	v_pk_fma_f32 v[80:81], v[80:81], v[16:17], v[84:85] op_sel_hi:[1,0,1]
	v_pk_fma_f32 v[78:79], v[78:79], v[16:17], v[86:87] op_sel_hi:[1,0,1]
	ds_write_b128 v82, v[78:81] offset:18496
	ds_read_b128 v[78:81], v82 offset:18560
	v_pk_mul_f32 v[84:85], v[70:71], v[36:37] op_sel_hi:[1,0]
	v_pk_mul_f32 v[86:87], v[68:69], v[36:37] op_sel_hi:[1,0]
	s_waitcnt lgkmcnt(0)
	v_pk_fma_f32 v[80:81], v[16:17], v[80:81], v[84:85] op_sel_hi:[0,1,1]
	v_pk_fma_f32 v[78:79], v[16:17], v[78:79], v[86:87] op_sel_hi:[0,1,1]
	ds_write_b128 v82, v[78:81] offset:18560
	ds_read_b128 v[78:81], v82 offset:18624
	s_waitcnt lgkmcnt(0)
	v_pk_mul_f32 v[80:81], v[16:17], v[80:81] op_sel_hi:[0,1]
	v_pk_mul_f32 v[78:79], v[16:17], v[78:79] op_sel_hi:[0,1]
	v_pk_fma_f32 v[80:81], v[74:75], v[36:37], v[80:81] op_sel_hi:[1,0,1]
	v_pk_fma_f32 v[78:79], v[72:73], v[36:37], v[78:79] op_sel_hi:[1,0,1]
	ds_write_b128 v82, v[78:81] offset:18624
	s_and_b64 exec, exec, s[38:39]
	s_cbranch_execz .LBB0_420
	v_add_f32_e32 v39, v39, v40
	v_mul_f32_e32 v36, v39, v36
	v_fmac_f32_e32 v36, v17, v16
	ds_write2st64_b32 v41, v42, v36 offset0:208 offset1:210
	s_branch .LBB0_420

	.amdhsa_kernel _Z14fwd_megakernel6Params
		.amdhsa_group_segment_fixed_size 79392
		.amdhsa_private_segment_fixed_size 0
		.amdhsa_kernarg_size 424
		.amdhsa_user_sgpr_count 2
		.amdhsa_user_sgpr_dispatch_ptr 0
		.amdhsa_user_sgpr_queue_ptr 0
		.amdhsa_user_sgpr_kernarg_segment_ptr 1
		.amdhsa_user_sgpr_dispatch_id 0
		.amdhsa_user_sgpr_kernarg_preload_length 0
		.amdhsa_user_sgpr_kernarg_preload_offset 0
		.amdhsa_user_sgpr_private_segment_size 0
		.amdhsa_uses_dynamic_stack 0
		.amdhsa_enable_private_segment 0
		.amdhsa_system_sgpr_workgroup_id_x 1
		.amdhsa_system_sgpr_workgroup_id_y 0
		.amdhsa_system_sgpr_workgroup_id_z 0
		.amdhsa_system_sgpr_workgroup_info 0
		.amdhsa_system_vgpr_workitem_id 2
		.amdhsa_next_free_vgpr 256
		.amdhsa_next_free_sgpr 102
		.amdhsa_accum_offset 256
		.amdhsa_reserve_vcc 1
		.amdhsa_float_round_mode_32 0
		.amdhsa_float_round_mode_16_64 0
		.amdhsa_float_denorm_mode_32 3
		.amdhsa_float_denorm_mode_16_64 3
		.amdhsa_dx10_clamp 1
		.amdhsa_ieee_mode 1
		.amdhsa_fp16_overflow 0
		.amdhsa_tg_split 0
		.amdhsa_exception_fp_ieee_invalid_op 0
		.amdhsa_exception_fp_denorm_src 0
		.amdhsa_exception_fp_ieee_div_zero 0
		.amdhsa_exception_fp_ieee_overflow 0
		.amdhsa_exception_fp_ieee_underflow 0
		.amdhsa_exception_fp_ieee_inexact 0
		.amdhsa_exception_int_div_zero 0
	.end_amdhsa_kernel

amdhsa.kernels:
  - .agpr_count:     0
    .args:
      - .offset:         0
        .size:           168
        .value_kind:     by_value
      - .offset:         168
        .size:           4
        .value_kind:     hidden_block_count_x
      - .offset:         172
        .size:           4
        .value_kind:     hidden_block_count_y
      - .offset:         176
        .size:           4
        .value_kind:     hidden_block_count_z
      - .offset:         180
        .size:           2
        .value_kind:     hidden_group_size_x
      - .offset:         182
        .size:           2
        .value_kind:     hidden_group_size_y
      - .offset:         184
        .size:           2
        .value_kind:     hidden_group_size_z
      - .offset:         186
        .size:           2
        .value_kind:     hidden_remainder_x
      - .offset:         188
        .size:           2
        .value_kind:     hidden_remainder_y
      - .offset:         190
        .size:           2
        .value_kind:     hidden_remainder_z
      - .offset:         208
        .size:           8
        .value_kind:     hidden_global_offset_x
      - .offset:         216
        .size:           8
        .value_kind:     hidden_global_offset_y
      - .offset:         224
        .size:           8
        .value_kind:     hidden_global_offset_z
      - .offset:         232
        .size:           2
        .value_kind:     hidden_grid_dims
      - .offset:         256
        .size:           8
        .value_kind:     hidden_multigrid_sync_arg
    .group_segment_fixed_size: 79392
    .kernarg_segment_align: 8
    .kernarg_segment_size: 424
    .language:       OpenCL C
    .language_version:
      - 2
      - 0
    .max_flat_workgroup_size: 256
    .name:           _Z14fwd_megakernel6Params
    .private_segment_fixed_size: 0
    .sgpr_count:     108
    .sgpr_spill_count: 165
    .symbol:         _Z14fwd_megakernel6Params.kd
    .uniform_work_group_size: 1
    .uses_dynamic_stack: false
    .vgpr_count:     256
    .vgpr_spill_count: 0
    .wavefront_size: 64
